# cleanup: redundant counted vmcnt waits and inline-asm pad nop removed from the attention P.V segments (on top of the ConvGLU neighbour-row simplification)
# speedup vs baseline: 1.0064x; 1.0064x over previous
; __device__ __forceinline__ void partialSM(f32x16& p0, f32x16& p1, float& m_reg, float& mn, float& alpha) {
;     constexpr float C = SCALE * 1.4426950408889634f;
;     float pmax = p0[0];
; #pragma unroll
;     for (int r = 1; r < 16; ++r) pmax = fmaxf(pmax, p0[r]);
; #pragma unroll
;     for (int r = 0; r < 16; ++r) pmax = fmaxf(pmax, p1[r]);
;     { auto rr = __builtin_amdgcn_permlane32_swap(__float_as_uint(pmax), __float_as_uint(pmax), false, false);
;       pmax = fmaxf(__uint_as_float(rr[0]), __uint_as_float(rr[1])); }
;     if (__builtin_expect(__all(pmax - m_reg <= THR / SCALE), 1)) { mn = m_reg; alpha = 1.f; }
;     else { mn = fmaxf(m_reg, pmax); alpha = __builtin_amdgcn_exp2f((m_reg - mn) * C); m_reg = mn; }
;     const float mnC = -mn * C;
; #pragma unroll
;     for (int r = 0; r < 16; ++r) p0[r] = fmaf(p0[r], C, mnC);
; #pragma unroll
;     for (int r = 0; r < 16; ++r) p1[r] = fmaf(p1[r], C, mnC);
; #pragma unroll
;     for (int r = 0; r < 16; ++r) p0[r] = __builtin_amdgcn_exp2f(p0[r]);
; }
; __device__ __forceinline__ void finishSM(f32x16& p0, f32x16& p1, float alpha, float& l_reg, bf16x8& pa0, bf16x8& pa1, bf16x8& pa2, bf16x8& pa3) {
; #pragma unroll
;     for (int r = 0; r < 16; ++r) p1[r] = __builtin_amdgcn_exp2f(p1[r]);
;     float ps = 0;
; #pragma unroll
;     for (int r = 0; r < 16; ++r) ps += p0[r];
; #pragma unroll
;     for (int r = 0; r < 16; ++r) ps += p1[r];
;     { auto rr = __builtin_amdgcn_permlane32_swap(__float_as_uint(ps), __float_as_uint(ps), false, false);
;       ps = __uint_as_float(rr[0]) + __uint_as_float(rr[1]); }
;     l_reg = l_reg * alpha + ps;
;     ...
;     PK4(p0, 0, pa0); PK4(p0, 8, pa1); PK4(p1, 0, pa2); PK4(p1, 8, pa3);
;     ...
; }
; __device__ __forceinline__ void qkt(f32x16& p0, f32x16& p1, const char* Ks, const bf16x8* qr, int r32, int hi, int comp) {
;     p0 = f32x16{}; p1 = f32x16{};
; #pragma unroll
;     for (int d0 = 0; d0 < 4; ++d0) { const int cb = (comp * 64 + d0 * 16 + hi * 8) * 2;
;         const bf16x8 b0 = *reinterpret_cast<const bf16x8*>(Ks + KSWZ(r32, cb));
;         const bf16x8 b1 = *reinterpret_cast<const bf16x8*>(Ks + KSWZ(32 + r32, cb));
;         p0 = __builtin_amdgcn_mfma_f32_32x32x16_bf16(b0, qr[d0], p0, 0, 0, 0);
;         p1 = __builtin_amdgcn_mfma_f32_32x32x16_bf16(b1, qr[d0], p1, 0, 0, 0); }
; }
.LBB0_262:
	ds_read_b128 v[64:67], v170 offset:49152
	ds_read_b128 v[68:71], v170 offset:57344
	v_add_f32_e32 v177, 0, v240
	v_add_f32_e32 v177, v241, v177
	v_add_f32_e32 v177, v242, v177
	s_waitcnt lgkmcnt(1)
	v_mfma_f32_32x32x16_bf16 v[80:95], v[64:67], v[110:113], 0
	v_add_f32_e32 v177, v243, v177
	v_add_f32_e32 v177, v244, v177
	ds_read_b128 v[178:181], v171 offset:49152
	ds_read_b128 v[220:223], v171 offset:57344
	v_add_f32_e32 v177, v245, v177
	v_add_f32_e32 v177, v246, v177
	v_add_f32_e32 v177, v247, v177
	v_add_f32_e32 v177, v248, v177
	s_waitcnt lgkmcnt(2)
	v_mfma_f32_32x32x16_bf16 v[64:79], v[68:71], v[110:113], 0
	v_add_f32_e32 v177, v249, v177
	v_add_f32_e32 v177, v250, v177
	v_add_f32_e32 v177, v251, v177
	v_exp_f32_e32 v128, v128
	v_add_f32_e32 v177, v206, v177
	v_exp_f32_e32 v129, v129
	v_add_f32_e32 v177, v207, v177
	s_waitcnt lgkmcnt(1)
	v_mfma_f32_32x32x16_bf16 v[80:95], v[178:181], v[106:109], v[80:95]
	v_exp_f32_e32 v126, v126
	v_add_f32_e32 v177, v208, v177
	v_exp_f32_e32 v127, v127
	v_add_f32_e32 v177, v209, v177
	v_exp_f32_e32 v122, v122
	v_add_f32_e32 v177, v128, v177
	v_exp_f32_e32 v123, v123
	s_waitcnt lgkmcnt(0)
	v_mfma_f32_32x32x16_bf16 v[64:79], v[220:223], v[106:109], v[64:79]
	ds_read_b128 v[178:181], v173 offset:49152
	ds_read_b128 v[220:223], v173 offset:57344
	v_add_f32_e32 v177, v129, v177
	v_exp_f32_e32 v118, v118
	v_add_f32_e32 v177, v126, v177
	v_exp_f32_e32 v119, v119
	v_add_f32_e32 v177, v127, v177
	v_exp_f32_e32 v116, v116
	s_waitcnt lgkmcnt(1)
	v_mfma_f32_32x32x16_bf16 v[80:95], v[178:181], v[102:105], v[80:95]
	v_add_f32_e32 v177, v122, v177
	v_exp_f32_e32 v117, v117
	v_add_f32_e32 v177, v123, v177
	v_exp_f32_e32 v124, v124
	v_add_f32_e32 v177, v118, v177
	v_exp_f32_e32 v125, v125
	v_add_f32_e32 v177, v119, v177
	s_waitcnt lgkmcnt(0)
	v_mfma_f32_32x32x16_bf16 v[64:79], v[220:223], v[102:105], v[64:79]
	ds_read_b128 v[178:181], v172 offset:49152
	ds_read_b128 v[220:223], v172 offset:57344
	v_exp_f32_e32 v120, v120
	v_add_f32_e32 v177, v116, v177
	v_exp_f32_e32 v121, v121
	v_add_f32_e32 v177, v117, v177
	v_exp_f32_e32 v114, v114
	v_add_f32_e32 v177, v124, v177
	s_waitcnt lgkmcnt(1)
	v_mfma_f32_32x32x16_bf16 v[80:95], v[178:181], v[98:101], v[80:95]
	v_exp_f32_e32 v115, v115
	v_add_f32_e32 v177, v125, v177
	v_add_f32_e32 v177, v120, v177
	v_add_f32_e32 v177, v121, v177
	v_add_f32_e32 v177, v114, v177
	v_add_f32_e32 v177, v115, v177
	v_mov_b32_e32 v178, v177
	s_waitcnt lgkmcnt(0)
	v_mfma_f32_32x32x16_bf16 v[64:79], v[220:223], v[98:101], v[64:79]
	v_cvt_pk_bf16_f32 v212, v240, v241
	v_cvt_pk_bf16_f32 v213, v242, v243
	v_cvt_pk_bf16_f32 v214, v244, v245
	v_cvt_pk_bf16_f32 v215, v246, v247
	v_cvt_pk_bf16_f32 v180, v248, v249
	v_cvt_pk_bf16_f32 v181, v250, v251
	v_cvt_pk_bf16_f32 v182, v206, v207
	v_permlane32_swap_b32_e32 v177, v178
	v_cvt_pk_bf16_f32 v183, v208, v209
	v_permlane32_swap_b32_e32 v180, v182
	v_cvt_pk_bf16_f32 v184, v128, v129
	v_cvt_pk_bf16_f32 v185, v126, v127
	v_cvt_pk_bf16_f32 v186, v122, v123
	v_cvt_pk_bf16_f32 v187, v118, v119
	v_cvt_pk_bf16_f32 v216, v116, v117
	v_cvt_pk_bf16_f32 v217, v124, v125
	v_cvt_pk_bf16_f32 v218, v120, v121
	v_cvt_pk_bf16_f32 v219, v114, v115
	v_permlane32_swap_b32_e32 v212, v214
	v_permlane32_swap_b32_e32 v213, v215
	v_permlane32_swap_b32_e32 v181, v183
	v_permlane32_swap_b32_e32 v184, v186
	v_permlane32_swap_b32_e32 v185, v187
	v_permlane32_swap_b32_e32 v216, v218
	v_permlane32_swap_b32_e32 v217, v219
	v_add_u32_e32 v122, 0x10000, v176
	global_load_dwordx4 v[240:243], v176, s[58:59]
	global_load_dwordx4 v[244:247], v176, s[28:29]
	global_load_dwordx4 v[206:209], v122, s[58:59]
	s_nop 0
	global_load_dwordx4 v[248:251], v122, s[28:29]
	ds_read_b64_tr_b16 v[220:221], v160 offset:0
	ds_read_b64_tr_b16 v[222:223], v160 offset:0x800
	ds_read_b64_tr_b16 v[224:225], v160 offset:0x1000
	ds_read_b64_tr_b16 v[226:227], v160 offset:0x1800
	ds_read_b64_tr_b16 v[228:229], v160 offset:0x2000
	ds_read_b64_tr_b16 v[230:231], v160 offset:0x2800
	ds_read_b64_tr_b16 v[232:233], v160 offset:0x3000
	ds_read_b64_tr_b16 v[234:235], v160 offset:0x3800
	s_waitcnt lgkmcnt(0)
	v_mfma_f32_32x32x16_bf16 v[48:63], v[212:215], v[220:223], v[48:63]
	ds_read_b64_tr_b16 v[220:221], v160 offset:0x200
	ds_read_b64_tr_b16 v[222:223], v160 offset:0xa00
	v_max_f32_e32 v179, v81, v81
	v_max_f32_e32 v255, v80, v80
	v_max_f32_e32 v179, v255, v179
	v_max3_f32 v179, v179, v82, v83
	v_max3_f32 v179, v179, v84, v85
	v_mfma_f32_32x32x16_bf16 v[48:63], v[180:183], v[224:227], v[48:63]
	ds_read_b64_tr_b16 v[224:225], v160 offset:0x1200
	ds_read_b64_tr_b16 v[226:227], v160 offset:0x1a00
	v_max3_f32 v179, v179, v86, v87
	v_max3_f32 v179, v179, v88, v89
	v_max3_f32 v179, v179, v90, v91
	v_max3_f32 v179, v179, v92, v93
	v_max3_f32 v179, v179, v94, v95
	v_mfma_f32_32x32x16_bf16 v[48:63], v[184:187], v[228:231], v[48:63]
	ds_read_b64_tr_b16 v[228:229], v160 offset:0x2200
	ds_read_b64_tr_b16 v[230:231], v160 offset:0x2a00
	v_max3_f32 v179, v179, v64, v65
	v_max3_f32 v179, v179, v66, v67
	v_max3_f32 v179, v179, v68, v69
	v_max3_f32 v179, v179, v70, v71
	v_max3_f32 v179, v179, v72, v73
	v_mfma_f32_32x32x16_bf16 v[48:63], v[216:219], v[232:235], v[48:63]
	ds_read_b64_tr_b16 v[232:233], v160 offset:0x3200
	ds_read_b64_tr_b16 v[234:235], v160 offset:0x3a00
	v_max3_f32 v179, v179, v74, v75
	v_max3_f32 v179, v179, v76, v77
	v_max3_f32 v179, v179, v78, v79
	v_mov_b32_e32 v255, v179
	s_nop 1
	v_permlane32_swap_b32_e32 v179, v255
	s_waitcnt lgkmcnt(0)
; __device__ __forceinline__ void partialSM(f32x16& p0, f32x16& p1, float& m_reg, float& mn, float& alpha) {
;     ...
;     { auto rr = __builtin_amdgcn_permlane32_swap(__float_as_uint(pmax), __float_as_uint(pmax), false, false);
;       pmax = fmaxf(__uint_as_float(rr[0]), __uint_as_float(rr[1])); }
;     if (__builtin_expect(__all(pmax - m_reg <= THR / SCALE), 1)) { mn = m_reg; alpha = 1.f; }
;     else { mn = fmaxf(m_reg, pmax); alpha = __builtin_amdgcn_exp2f((m_reg - mn) * C); m_reg = mn; }
;     const float mnC = -mn * C;
; #pragma unroll
;     for (int r = 0; r < 16; ++r) p0[r] = fmaf(p0[r], C, mnC);
; #pragma unroll
;     for (int r = 0; r < 16; ++r) p1[r] = fmaf(p1[r], C, mnC);
; #pragma unroll
;     for (int r = 0; r < 16; ++r) p0[r] = __builtin_amdgcn_exp2f(p0[r]);
; }
	v_mfma_f32_32x32x16_bf16 v[32:47], v[212:215], v[220:223], v[32:47]
	ds_read_b64_tr_b16 v[220:221], v160 offset:0x400
	ds_read_b64_tr_b16 v[222:223], v160 offset:0xc00
	v_max_f32_e32 v255, v255, v255
	v_max_f32_e32 v179, v179, v179
	v_max_f32_e32 v179, v179, v255
	v_sub_f32_e32 v255, v179, v175
	v_cmp_ge_f32_e32 vcc, s65, v255
	v_mfma_f32_32x32x16_bf16 v[32:47], v[180:183], v[224:227], v[32:47]
	ds_read_b64_tr_b16 v[224:225], v160 offset:0x1400
	ds_read_b64_tr_b16 v[226:227], v160 offset:0x1c00
	v_max_f32_e32 v255, v175, v175
	v_max_f32_e32 v179, v255, v179
	v_sub_f32_e32 v255, v175, v179
	v_mul_f32_e32 v255, 0x3e38aa3b, v255
	v_exp_f32_e32 v255, v255
	v_mfma_f32_32x32x16_bf16 v[32:47], v[184:187], v[228:231], v[32:47]
	ds_read_b64_tr_b16 v[228:229], v160 offset:0x2400
	ds_read_b64_tr_b16 v[230:231], v160 offset:0x2c00
	s_cmp_eq_u64 vcc, exec
	s_cselect_b64 s[8:9], -1, 0
	v_cndmask_b32_e64 v255, v255, 1.0, s[8:9]
	v_cndmask_b32_e64 v175, v179, v175, s[8:9]
	v_mul_f32_e32 v179, 0xbe38aa3b, v175
	v_mfma_f32_32x32x16_bf16 v[32:47], v[216:219], v[232:235], v[32:47]
	ds_read_b64_tr_b16 v[232:233], v160 offset:0x3400
	ds_read_b64_tr_b16 v[234:235], v160 offset:0x3c00
	v_pk_fma_f32 v[80:81], v[80:81], s[72:73], v[178:179] op_sel:[0,0,1] op_sel_hi:[1,0,1]
	v_pk_fma_f32 v[82:83], v[82:83], s[72:73], v[178:179] op_sel:[0,0,1] op_sel_hi:[1,0,1]
	v_pk_fma_f32 v[84:85], v[84:85], s[72:73], v[178:179] op_sel:[0,0,1] op_sel_hi:[1,0,1]
	v_pk_fma_f32 v[86:87], v[86:87], s[72:73], v[178:179] op_sel:[0,0,1] op_sel_hi:[1,0,1]
	v_pk_fma_f32 v[88:89], v[88:89], s[72:73], v[178:179] op_sel:[0,0,1] op_sel_hi:[1,0,1]
	s_waitcnt lgkmcnt(0)
	v_mfma_f32_32x32x16_bf16 v[16:31], v[212:215], v[220:223], v[16:31]
	ds_read_b64_tr_b16 v[220:221], v160 offset:0x600
	ds_read_b64_tr_b16 v[222:223], v160 offset:0xe00
	v_pk_fma_f32 v[90:91], v[90:91], s[72:73], v[178:179] op_sel:[0,0,1] op_sel_hi:[1,0,1]
	v_pk_fma_f32 v[92:93], v[92:93], s[72:73], v[178:179] op_sel:[0,0,1] op_sel_hi:[1,0,1]
	v_pk_fma_f32 v[94:95], v[94:95], s[72:73], v[178:179] op_sel:[0,0,1] op_sel_hi:[1,0,1]
	v_exp_f32_e32 v127, v80
	v_mfma_f32_32x32x16_bf16 v[16:31], v[180:183], v[224:227], v[16:31]
	ds_read_b64_tr_b16 v[224:225], v160 offset:0x1600
	ds_read_b64_tr_b16 v[226:227], v160 offset:0x1e00
	v_exp_f32_e32 v129, v81
	v_exp_f32_e32 v125, v82
	v_exp_f32_e32 v128, v83
	v_mfma_f32_32x32x16_bf16 v[16:31], v[184:187], v[228:231], v[16:31]
	ds_read_b64_tr_b16 v[228:229], v160 offset:0x2600
	ds_read_b64_tr_b16 v[230:231], v160 offset:0x2e00
	v_exp_f32_e32 v123, v84
	v_exp_f32_e32 v126, v85
	v_exp_f32_e32 v122, v86
	v_mfma_f32_32x32x16_bf16 v[16:31], v[216:219], v[232:235], v[16:31]
	ds_read_b64_tr_b16 v[232:233], v160 offset:0x3600
	ds_read_b64_tr_b16 v[234:235], v160 offset:0x3e00
	v_exp_f32_e32 v124, v87
	v_exp_f32_e32 v119, v88
	v_exp_f32_e32 v121, v89
	s_waitcnt lgkmcnt(0)
	v_mfma_f32_32x32x16_bf16 v[0:15], v[212:215], v[220:223], v[0:15]
	s_barrier
	s_waitcnt vmcnt(0)
	ds_write_b128 v163, v[240:243]
	ds_write_b128 v164, v[206:209]
	ds_write_b128 v161, v[244:247] offset:32768
	ds_write_b128 v162, v[248:251] offset:32768
	v_exp_f32_e32 v117, v90
	v_exp_f32_e32 v120, v91
	v_exp_f32_e32 v115, v92
	v_mfma_f32_32x32x16_bf16 v[0:15], v[180:183], v[224:227], v[0:15]
	v_exp_f32_e32 v118, v93
	v_exp_f32_e32 v114, v94
	v_exp_f32_e32 v116, v95
	v_mfma_f32_32x32x16_bf16 v[0:15], v[184:187], v[228:231], v[0:15]
	v_mfma_f32_32x32x16_bf16 v[0:15], v[216:219], v[232:235], v[0:15]
	v_mov_b32_e32 v180, v255
	v_cmp_gt_f32_e32 vcc, 1.0, v180
	s_cbranch_vccz .LBB0_266
	s_and_saveexec_b64 s[2:3], s[6:7]
	ds_write_b32 v157, v180 offset:128
	s_or_b64 exec, exec, s[2:3]
	s_waitcnt lgkmcnt(0)
	ds_read_b128 v[240:243], v158 offset:224
	ds_read_b128 v[244:247], v158 offset:192
	ds_read_b128 v[248:251], v158 offset:160
	ds_read_b128 v[206:209], v158 offset:128
	s_waitcnt lgkmcnt(3)
	v_pk_mul_f32 v[62:63], v[62:63], v[242:243]
	s_waitcnt lgkmcnt(2)
	v_pk_mul_f32 v[58:59], v[58:59], v[246:247]
	s_waitcnt lgkmcnt(1)
	v_pk_mul_f32 v[54:55], v[54:55], v[250:251]
	s_waitcnt lgkmcnt(0)
	v_pk_mul_f32 v[50:51], v[50:51], v[208:209]
	v_pk_mul_f32 v[60:61], v[60:61], v[240:241]
	v_pk_mul_f32 v[56:57], v[56:57], v[244:245]
	v_pk_mul_f32 v[52:53], v[52:53], v[248:249]
	v_pk_mul_f32 v[48:49], v[48:49], v[206:207]
	v_pk_mul_f32 v[46:47], v[46:47], v[242:243]
	v_pk_mul_f32 v[42:43], v[42:43], v[246:247]
	v_pk_mul_f32 v[38:39], v[38:39], v[250:251]
	v_pk_mul_f32 v[34:35], v[34:35], v[208:209]
	v_pk_mul_f32 v[44:45], v[44:45], v[240:241]
	v_pk_mul_f32 v[40:41], v[40:41], v[244:245]
	v_pk_mul_f32 v[36:37], v[36:37], v[248:249]
	v_pk_mul_f32 v[32:33], v[32:33], v[206:207]
	v_pk_mul_f32 v[30:31], v[30:31], v[242:243]
	v_pk_mul_f32 v[26:27], v[26:27], v[246:247]
	v_pk_mul_f32 v[22:23], v[22:23], v[250:251]
	v_pk_mul_f32 v[18:19], v[18:19], v[208:209]
	v_pk_mul_f32 v[28:29], v[28:29], v[240:241]
	v_pk_mul_f32 v[24:25], v[24:25], v[244:245]
	v_pk_mul_f32 v[20:21], v[20:21], v[248:249]
	v_pk_mul_f32 v[16:17], v[16:17], v[206:207]
	v_pk_mul_f32 v[14:15], v[14:15], v[242:243]
	v_pk_mul_f32 v[10:11], v[10:11], v[246:247]
	v_pk_mul_f32 v[6:7], v[6:7], v[250:251]
	v_pk_mul_f32 v[2:3], v[2:3], v[208:209]
	v_pk_mul_f32 v[12:13], v[12:13], v[240:241]
	v_pk_mul_f32 v[8:9], v[8:9], v[244:245]
	v_pk_mul_f32 v[4:5], v[4:5], v[248:249]
	v_pk_mul_f32 v[0:1], v[0:1], v[206:207]
; __device__ __forceinline__ void partialSM(f32x16& p0, f32x16& p1, float& m_reg, float& mn, float& alpha) {
;     constexpr float C = SCALE * 1.4426950408889634f;
;     float pmax = p0[0];
; #pragma unroll
;     for (int r = 1; r < 16; ++r) pmax = fmaxf(pmax, p0[r]);
; #pragma unroll
;     for (int r = 0; r < 16; ++r) pmax = fmaxf(pmax, p1[r]);
;     { auto rr = __builtin_amdgcn_permlane32_swap(__float_as_uint(pmax), __float_as_uint(pmax), false, false);
;       pmax = fmaxf(__uint_as_float(rr[0]), __uint_as_float(rr[1])); }
;     if (__builtin_expect(__all(pmax - m_reg <= THR / SCALE), 1)) { mn = m_reg; alpha = 1.f; }
;     else { mn = fmaxf(m_reg, pmax); alpha = __builtin_amdgcn_exp2f((m_reg - mn) * C); m_reg = mn; }
;     const float mnC = -mn * C;
; #pragma unroll
;     for (int r = 0; r < 16; ++r) p0[r] = fmaf(p0[r], C, mnC);
; #pragma unroll
;     for (int r = 0; r < 16; ++r) p1[r] = fmaf(p1[r], C, mnC);
; #pragma unroll
;     for (int r = 0; r < 16; ++r) p0[r] = __builtin_amdgcn_exp2f(p0[r]);
; }
; __device__ __forceinline__ void finishSM(f32x16& p0, f32x16& p1, float alpha, float& l_reg, bf16x8& pa0, bf16x8& pa1, bf16x8& pa2, bf16x8& pa3) {
; #pragma unroll
;     for (int r = 0; r < 16; ++r) p1[r] = __builtin_amdgcn_exp2f(p1[r]);
;     float ps = 0;
; #pragma unroll
;     for (int r = 0; r < 16; ++r) ps += p0[r];
; #pragma unroll
;     for (int r = 0; r < 16; ++r) ps += p1[r];
;     { auto rr = __builtin_amdgcn_permlane32_swap(__float_as_uint(ps), __float_as_uint(ps), false, false);
;       ps = __uint_as_float(rr[0]) + __uint_as_float(rr[1]); }
;     l_reg = l_reg * alpha + ps;
;     ...
;     PK4(p0, 0, pa0); PK4(p0, 8, pa1); PK4(p1, 0, pa2); PK4(p1, 8, pa3);
;     ...
; }
; __device__ __forceinline__ void qkt(f32x16& p0, f32x16& p1, const char* Ks, const bf16x8* qr, int r32, int hi, int comp) {
;     p0 = f32x16{}; p1 = f32x16{};
; #pragma unroll
;     for (int d0 = 0; d0 < 4; ++d0) { const int cb = (comp * 64 + d0 * 16 + hi * 8) * 2;
;         const bf16x8 b0 = *reinterpret_cast<const bf16x8*>(Ks + KSWZ(r32, cb));
;         const bf16x8 b1 = *reinterpret_cast<const bf16x8*>(Ks + KSWZ(32 + r32, cb));
;         p0 = __builtin_amdgcn_mfma_f32_32x32x16_bf16(b0, qr[d0], p0, 0, 0, 0);
;         p1 = __builtin_amdgcn_mfma_f32_32x32x16_bf16(b1, qr[d0], p1, 0, 0, 0); }
; }
.LBB0_266:
	v_fmamk_f32 v189, v64, 0x3e38aa3b, v179
	v_fmamk_f32 v211, v65, 0x3e38aa3b, v179
	v_fmamk_f32 v212, v66, 0x3e38aa3b, v179
	v_fmamk_f32 v213, v67, 0x3e38aa3b, v179
	v_fmamk_f32 v214, v68, 0x3e38aa3b, v179
	v_fmamk_f32 v182, v69, 0x3e38aa3b, v179
	v_fmamk_f32 v183, v70, 0x3e38aa3b, v179
	v_fmamk_f32 v184, v71, 0x3e38aa3b, v179
	v_fmamk_f32 v185, v72, 0x3e38aa3b, v179
	v_fmamk_f32 v186, v73, 0x3e38aa3b, v179
	v_fmamk_f32 v187, v74, 0x3e38aa3b, v179
	v_fmamk_f32 v188, v75, 0x3e38aa3b, v179
	v_fmamk_f32 v181, v76, 0x3e38aa3b, v179
	v_fmamk_f32 v215, v77, 0x3e38aa3b, v179
	v_fmamk_f32 v216, v78, 0x3e38aa3b, v179
	v_fmac_f32_e32 v179, 0x3e38aa3b, v79
	s_waitcnt lgkmcnt(0)
	s_barrier
	ds_read_b128 v[64:67], v170 offset:32768
	ds_read_b128 v[68:71], v170 offset:40960
	v_exp_f32_e32 v203, v181
	v_add_f32_e32 v181, 0, v127
	v_add_f32_e32 v181, v129, v181
	s_waitcnt lgkmcnt(1)
	v_mfma_f32_32x32x16_bf16 v[80:95], v[64:67], v[110:113], 0
	v_add_f32_e32 v181, v125, v181
	v_add_f32_e32 v181, v128, v181
	v_add_f32_e32 v181, v123, v181
	ds_read_b128 v[218:221], v171 offset:32768
	ds_read_b128 v[222:225], v171 offset:40960
	v_add_f32_e32 v181, v126, v181
	v_add_f32_e32 v181, v122, v181
	v_add_f32_e32 v181, v124, v181
	s_waitcnt lgkmcnt(2)
	v_mfma_f32_32x32x16_bf16 v[64:79], v[68:71], v[110:113], 0
	v_add_f32_e32 v181, v119, v181
	v_add_f32_e32 v181, v121, v181
	v_add_f32_e32 v181, v117, v181
	v_add_f32_e32 v181, v120, v181
	v_exp_f32_e32 v189, v189
	v_add_f32_e32 v181, v115, v181
	v_exp_f32_e32 v190, v211
	s_waitcnt lgkmcnt(1)
	v_mfma_f32_32x32x16_bf16 v[80:95], v[218:221], v[106:109], v[80:95]
	v_add_f32_e32 v181, v118, v181
	v_exp_f32_e32 v191, v212
	v_add_f32_e32 v181, v114, v181
	v_exp_f32_e32 v192, v213
	v_add_f32_e32 v181, v116, v181
	v_exp_f32_e32 v193, v214
	v_add_f32_e32 v181, v189, v181
	s_waitcnt lgkmcnt(0)
	v_mfma_f32_32x32x16_bf16 v[64:79], v[222:225], v[106:109], v[64:79]
	ds_read_b128 v[218:221], v173 offset:32768
	ds_read_b128 v[222:225], v173 offset:40960
	v_exp_f32_e32 v194, v182
	v_add_f32_e32 v181, v190, v181
	v_exp_f32_e32 v183, v183
	v_add_f32_e32 v181, v191, v181
	v_exp_f32_e32 v195, v184
	v_add_f32_e32 v181, v192, v181
	s_waitcnt lgkmcnt(1)
	v_mfma_f32_32x32x16_bf16 v[80:95], v[218:221], v[102:105], v[80:95]
	v_exp_f32_e32 v200, v185
	v_add_f32_e32 v181, v193, v181
	v_exp_f32_e32 v201, v186
	v_add_f32_e32 v181, v194, v181
	v_exp_f32_e32 v202, v187
	v_add_f32_e32 v181, v183, v181
	v_exp_f32_e32 v188, v188
	s_waitcnt lgkmcnt(0)
	v_mfma_f32_32x32x16_bf16 v[64:79], v[222:225], v[102:105], v[64:79]
	ds_read_b128 v[218:221], v172 offset:32768
	ds_read_b128 v[222:225], v172 offset:40960
	v_add_f32_e32 v181, v195, v181
	v_add_f32_e32 v181, v200, v181
	v_exp_f32_e32 v204, v215
	v_add_f32_e32 v181, v201, v181
	v_exp_f32_e32 v205, v216
	v_add_f32_e32 v181, v202, v181
	s_waitcnt lgkmcnt(1)
	v_mfma_f32_32x32x16_bf16 v[80:95], v[218:221], v[98:101], v[80:95]
	v_exp_f32_e32 v179, v179
	v_add_f32_e32 v181, v188, v181
	v_add_f32_e32 v181, v203, v181
	v_add_f32_e32 v181, v204, v181
	v_add_f32_e32 v181, v205, v181
	v_add_f32_e32 v181, v179, v181
	v_mov_b32_e32 v182, v181
	s_waitcnt lgkmcnt(0)
	v_mfma_f32_32x32x16_bf16 v[64:79], v[222:225], v[98:101], v[64:79]
	v_permlane32_swap_b32_e32 v181, v182
	v_cvt_pk_bf16_f32 v184, v127, v129
	v_cvt_pk_bf16_f32 v185, v125, v128
	v_cvt_pk_bf16_f32 v186, v123, v126
	v_cvt_pk_bf16_f32 v187, v122, v124
	v_cvt_pk_bf16_f32 v212, v119, v121
	v_cvt_pk_bf16_f32 v213, v117, v120
	v_cvt_pk_bf16_f32 v214, v115, v118
	v_cvt_pk_bf16_f32 v215, v114, v116
	v_cvt_pk_bf16_f32 v216, v189, v190
	v_cvt_pk_bf16_f32 v217, v191, v192
	v_cvt_pk_bf16_f32 v218, v193, v194
	v_cvt_pk_bf16_f32 v219, v183, v195
	v_cvt_pk_bf16_f32 v220, v200, v201
	v_cvt_pk_bf16_f32 v221, v202, v188
	v_cvt_pk_bf16_f32 v222, v203, v204
	v_cvt_pk_bf16_f32 v223, v205, v179
	s_nop 0
	v_permlane32_swap_b32_e32 v184, v186
	v_permlane32_swap_b32_e32 v185, v187
	v_permlane32_swap_b32_e32 v212, v214
	v_permlane32_swap_b32_e32 v213, v215
	v_permlane32_swap_b32_e32 v216, v218
	v_permlane32_swap_b32_e32 v217, v219
	v_permlane32_swap_b32_e32 v220, v222
	v_permlane32_swap_b32_e32 v221, v223
	v_add_u32_e32 v118, 0x20000, v176
	v_add_u32_e32 v122, 0x30000, v176
	global_load_dwordx4 v[114:117], v118, s[58:59]
	s_nop 0
	global_load_dwordx4 v[118:121], v118, s[28:29]
	s_nop 0
	global_load_dwordx4 v[126:129], v122, s[58:59]
	s_nop 0
	global_load_dwordx4 v[122:125], v122, s[28:29]
	ds_read_b64_tr_b16 v[224:225], v159 offset:0
	ds_read_b64_tr_b16 v[226:227], v159 offset:0x800
	ds_read_b64_tr_b16 v[228:229], v159 offset:0x1000
	ds_read_b64_tr_b16 v[230:231], v159 offset:0x1800
	ds_read_b64_tr_b16 v[232:233], v159 offset:0x2000
	ds_read_b64_tr_b16 v[234:235], v159 offset:0x2800
	ds_read_b64_tr_b16 v[236:237], v159 offset:0x3000
	ds_read_b64_tr_b16 v[238:239], v159 offset:0x3800
	s_waitcnt lgkmcnt(0)
	v_mfma_f32_32x32x16_bf16 v[48:63], v[184:187], v[224:227], v[48:63]
	ds_read_b64_tr_b16 v[224:225], v159 offset:0x200
	ds_read_b64_tr_b16 v[226:227], v159 offset:0xa00
	v_max_f32_e32 v255, v81, v81
	v_max_f32_e32 v210, v80, v80
	v_max_f32_e32 v255, v210, v255
	v_max3_f32 v255, v255, v82, v83
	v_max3_f32 v255, v255, v84, v85
	v_mfma_f32_32x32x16_bf16 v[48:63], v[212:215], v[228:231], v[48:63]
	ds_read_b64_tr_b16 v[228:229], v159 offset:0x1200
	ds_read_b64_tr_b16 v[230:231], v159 offset:0x1a00
	v_max3_f32 v255, v255, v86, v87
	v_max3_f32 v255, v255, v88, v89
	v_max3_f32 v255, v255, v90, v91
	v_max3_f32 v255, v255, v92, v93
	v_max3_f32 v255, v255, v94, v95
	v_mfma_f32_32x32x16_bf16 v[48:63], v[216:219], v[232:235], v[48:63]
	ds_read_b64_tr_b16 v[232:233], v159 offset:0x2200
	ds_read_b64_tr_b16 v[234:235], v159 offset:0x2a00
	v_max3_f32 v255, v255, v64, v65
	v_max3_f32 v255, v255, v66, v67
	v_max3_f32 v255, v255, v68, v69
	v_max3_f32 v255, v255, v70, v71
	v_max3_f32 v255, v255, v72, v73
	v_mfma_f32_32x32x16_bf16 v[48:63], v[220:223], v[236:239], v[48:63]
	ds_read_b64_tr_b16 v[236:237], v159 offset:0x3200
	ds_read_b64_tr_b16 v[238:239], v159 offset:0x3a00
	v_max3_f32 v255, v255, v74, v75
	v_max3_f32 v255, v255, v76, v77
	v_max3_f32 v255, v255, v78, v79
	v_mov_b32_e32 v210, v255
	s_nop 1
	v_permlane32_swap_b32_e32 v255, v210
	s_waitcnt lgkmcnt(0)
; __device__ __forceinline__ void partialSM(f32x16& p0, f32x16& p1, float& m_reg, float& mn, float& alpha) {
;     ...
;     { auto rr = __builtin_amdgcn_permlane32_swap(__float_as_uint(pmax), __float_as_uint(pmax), false, false);
;       pmax = fmaxf(__uint_as_float(rr[0]), __uint_as_float(rr[1])); }
;     if (__builtin_expect(__all(pmax - m_reg <= THR / SCALE), 1)) { mn = m_reg; alpha = 1.f; }
;     else { mn = fmaxf(m_reg, pmax); alpha = __builtin_amdgcn_exp2f((m_reg - mn) * C); m_reg = mn; }
;     const float mnC = -mn * C;
; #pragma unroll
;     for (int r = 0; r < 16; ++r) p0[r] = fmaf(p0[r], C, mnC);
; #pragma unroll
;     for (int r = 0; r < 16; ++r) p1[r] = fmaf(p1[r], C, mnC);
; #pragma unroll
;     for (int r = 0; r < 16; ++r) p0[r] = __builtin_amdgcn_exp2f(p0[r]);
; }
	v_mfma_f32_32x32x16_bf16 v[32:47], v[184:187], v[224:227], v[32:47]
	ds_read_b64_tr_b16 v[224:225], v159 offset:0x400
	ds_read_b64_tr_b16 v[226:227], v159 offset:0xc00
	v_max_f32_e32 v210, v210, v210
	v_max_f32_e32 v255, v255, v255
	v_max_f32_e32 v255, v255, v210
	v_sub_f32_e32 v210, v255, v175
	v_cmp_ge_f32_e32 vcc, s65, v210
	v_mfma_f32_32x32x16_bf16 v[32:47], v[212:215], v[228:231], v[32:47]
	ds_read_b64_tr_b16 v[228:229], v159 offset:0x1400
	ds_read_b64_tr_b16 v[230:231], v159 offset:0x1c00
	v_max_f32_e32 v210, v175, v175
	v_max_f32_e32 v210, v210, v255
	v_sub_f32_e32 v255, v175, v210
	v_mul_f32_e32 v255, 0x3e38aa3b, v255
	v_exp_f32_e32 v255, v255
	v_mfma_f32_32x32x16_bf16 v[32:47], v[216:219], v[232:235], v[32:47]
	ds_read_b64_tr_b16 v[232:233], v159 offset:0x2400
	ds_read_b64_tr_b16 v[234:235], v159 offset:0x2c00
	s_cmp_eq_u64 vcc, exec
	s_cselect_b64 s[8:9], -1, 0
	v_cndmask_b32_e64 v255, v255, 1.0, s[8:9]
	v_cndmask_b32_e64 v175, v210, v175, s[8:9]
	v_mul_f32_e32 v210, 0xbe38aa3b, v175
	v_mfma_f32_32x32x16_bf16 v[32:47], v[220:223], v[236:239], v[32:47]
	ds_read_b64_tr_b16 v[236:237], v159 offset:0x3400
	ds_read_b64_tr_b16 v[238:239], v159 offset:0x3c00
	v_pk_fma_f32 v[80:81], v[80:81], s[72:73], v[210:211] op_sel_hi:[1,0,0]
	v_pk_fma_f32 v[82:83], v[82:83], s[72:73], v[210:211] op_sel_hi:[1,0,0]
	v_pk_fma_f32 v[84:85], v[84:85], s[72:73], v[210:211] op_sel_hi:[1,0,0]
	v_pk_fma_f32 v[86:87], v[86:87], s[72:73], v[210:211] op_sel_hi:[1,0,0]
	v_pk_fma_f32 v[88:89], v[88:89], s[72:73], v[210:211] op_sel_hi:[1,0,0]
	s_waitcnt lgkmcnt(0)
	v_mfma_f32_32x32x16_bf16 v[16:31], v[184:187], v[224:227], v[16:31]
	ds_read_b64_tr_b16 v[224:225], v159 offset:0x600
	ds_read_b64_tr_b16 v[226:227], v159 offset:0xe00
	v_pk_fma_f32 v[90:91], v[90:91], s[72:73], v[210:211] op_sel_hi:[1,0,0]
	v_pk_fma_f32 v[92:93], v[92:93], s[72:73], v[210:211] op_sel_hi:[1,0,0]
	v_pk_fma_f32 v[94:95], v[94:95], s[72:73], v[210:211] op_sel_hi:[1,0,0]
	v_exp_f32_e32 v240, v80
	v_mfma_f32_32x32x16_bf16 v[16:31], v[212:215], v[228:231], v[16:31]
	ds_read_b64_tr_b16 v[228:229], v159 offset:0x1600
	ds_read_b64_tr_b16 v[230:231], v159 offset:0x1e00
	v_exp_f32_e32 v241, v81
	v_exp_f32_e32 v242, v82
	v_exp_f32_e32 v243, v83
	v_mfma_f32_32x32x16_bf16 v[16:31], v[216:219], v[232:235], v[16:31]
	ds_read_b64_tr_b16 v[232:233], v159 offset:0x2600
	ds_read_b64_tr_b16 v[234:235], v159 offset:0x2e00
	v_exp_f32_e32 v244, v84
	v_exp_f32_e32 v245, v85
	v_exp_f32_e32 v246, v86
	v_mfma_f32_32x32x16_bf16 v[16:31], v[220:223], v[236:239], v[16:31]
	ds_read_b64_tr_b16 v[236:237], v159 offset:0x3600
	ds_read_b64_tr_b16 v[238:239], v159 offset:0x3e00
	v_exp_f32_e32 v247, v87
	v_exp_f32_e32 v248, v88
	v_exp_f32_e32 v249, v89
	s_waitcnt lgkmcnt(0)
	v_mfma_f32_32x32x16_bf16 v[0:15], v[184:187], v[224:227], v[0:15]
	s_barrier
	s_waitcnt vmcnt(0)
	ds_write_b128 v163, v[114:117] offset:16384
	ds_write_b128 v164, v[126:129] offset:16384
	ds_write_b128 v161, v[118:121] offset:49152
	ds_write_b128 v162, v[122:125] offset:49152
	v_exp_f32_e32 v250, v90
	v_exp_f32_e32 v251, v91
	v_exp_f32_e32 v206, v92
	v_mfma_f32_32x32x16_bf16 v[0:15], v[212:215], v[228:231], v[0:15]
	v_exp_f32_e32 v207, v93
	v_exp_f32_e32 v208, v94
	v_exp_f32_e32 v209, v95
	v_mfma_f32_32x32x16_bf16 v[0:15], v[216:219], v[232:235], v[0:15]
	v_mfma_f32_32x32x16_bf16 v[0:15], v[220:223], v[236:239], v[0:15]
	v_mov_b32_e32 v179, v255
	v_cmp_gt_f32_e32 vcc, 1.0, v179
	s_cbranch_vccz .LBB0_270
	s_and_saveexec_b64 s[2:3], s[6:7]
	ds_write_b32 v157, v179 offset:128
	s_or_b64 exec, exec, s[2:3]
	s_waitcnt lgkmcnt(0)
	ds_read_b128 v[114:117], v158 offset:224
	ds_read_b128 v[118:121], v158 offset:192
	ds_read_b128 v[122:125], v158 offset:160
	ds_read_b128 v[126:129], v158 offset:128
	s_waitcnt lgkmcnt(3)
	v_pk_mul_f32 v[62:63], v[62:63], v[116:117]
	s_waitcnt lgkmcnt(2)
	v_pk_mul_f32 v[58:59], v[58:59], v[120:121]
	s_waitcnt lgkmcnt(1)
	v_pk_mul_f32 v[54:55], v[54:55], v[124:125]
	s_waitcnt lgkmcnt(0)
	v_pk_mul_f32 v[50:51], v[50:51], v[128:129]
	v_pk_mul_f32 v[60:61], v[60:61], v[114:115]
	v_pk_mul_f32 v[56:57], v[56:57], v[118:119]
	v_pk_mul_f32 v[52:53], v[52:53], v[122:123]
	v_pk_mul_f32 v[48:49], v[48:49], v[126:127]
	v_pk_mul_f32 v[46:47], v[46:47], v[116:117]
	v_pk_mul_f32 v[42:43], v[42:43], v[120:121]
	v_pk_mul_f32 v[38:39], v[38:39], v[124:125]
	v_pk_mul_f32 v[34:35], v[34:35], v[128:129]
	v_pk_mul_f32 v[44:45], v[44:45], v[114:115]
	v_pk_mul_f32 v[40:41], v[40:41], v[118:119]
	v_pk_mul_f32 v[36:37], v[36:37], v[122:123]
	v_pk_mul_f32 v[32:33], v[32:33], v[126:127]
	v_pk_mul_f32 v[30:31], v[30:31], v[116:117]
	v_pk_mul_f32 v[26:27], v[26:27], v[120:121]
	v_pk_mul_f32 v[22:23], v[22:23], v[124:125]
	v_pk_mul_f32 v[18:19], v[18:19], v[128:129]
	v_pk_mul_f32 v[28:29], v[28:29], v[114:115]
	v_pk_mul_f32 v[24:25], v[24:25], v[118:119]
	v_pk_mul_f32 v[20:21], v[20:21], v[122:123]
	v_pk_mul_f32 v[16:17], v[16:17], v[126:127]
	v_pk_mul_f32 v[14:15], v[14:15], v[116:117]
	v_pk_mul_f32 v[10:11], v[10:11], v[120:121]
	v_pk_mul_f32 v[6:7], v[6:7], v[124:125]
	v_pk_mul_f32 v[2:3], v[2:3], v[128:129]
	v_pk_mul_f32 v[12:13], v[12:13], v[114:115]
	v_pk_mul_f32 v[8:9], v[8:9], v[118:119]
	v_pk_mul_f32 v[4:5], v[4:5], v[122:123]
	v_pk_mul_f32 v[0:1], v[0:1], v[126:127]

; __device__ __forceinline__ void partialSM(f32x16& p0, f32x16& p1, float& m_reg, float& mn, float& alpha) {
;     constexpr float C = SCALE * 1.4426950408889634f;
;     float pmax = p0[0];
; #pragma unroll
;     for (int r = 1; r < 16; ++r) pmax = fmaxf(pmax, p0[r]);
; #pragma unroll
;     for (int r = 0; r < 16; ++r) pmax = fmaxf(pmax, p1[r]);
;     { auto rr = __builtin_amdgcn_permlane32_swap(__float_as_uint(pmax), __float_as_uint(pmax), false, false);
;       pmax = fmaxf(__uint_as_float(rr[0]), __uint_as_float(rr[1])); }
;     if (__builtin_expect(__all(pmax - m_reg <= THR / SCALE), 1)) { mn = m_reg; alpha = 1.f; }
;     else { mn = fmaxf(m_reg, pmax); alpha = __builtin_amdgcn_exp2f((m_reg - mn) * C); m_reg = mn; }
;     const float mnC = -mn * C;
; #pragma unroll
;     for (int r = 0; r < 16; ++r) p0[r] = fmaf(p0[r], C, mnC);
; #pragma unroll
;     for (int r = 0; r < 16; ++r) p1[r] = fmaf(p1[r], C, mnC);
; #pragma unroll
;     for (int r = 0; r < 16; ++r) p0[r] = __builtin_amdgcn_exp2f(p0[r]);
; }
; __device__ __forceinline__ void finishSM(f32x16& p0, f32x16& p1, float alpha, float& l_reg, bf16x8& pa0, bf16x8& pa1, bf16x8& pa2, bf16x8& pa3) {
; #pragma unroll
;     for (int r = 0; r < 16; ++r) p1[r] = __builtin_amdgcn_exp2f(p1[r]);
;     float ps = 0;
; #pragma unroll
;     for (int r = 0; r < 16; ++r) ps += p0[r];
; #pragma unroll
;     for (int r = 0; r < 16; ++r) ps += p1[r];
;     { auto rr = __builtin_amdgcn_permlane32_swap(__float_as_uint(ps), __float_as_uint(ps), false, false);
;       ps = __uint_as_float(rr[0]) + __uint_as_float(rr[1]); }
;     l_reg = l_reg * alpha + ps;
;     ...
;     PK4(p0, 0, pa0); PK4(p0, 8, pa1); PK4(p1, 0, pa2); PK4(p1, 8, pa3);
;     ...
; }
; __device__ __forceinline__ void qkt(f32x16& p0, f32x16& p1, const char* Ks, const bf16x8* qr, int r32, int hi, int comp) {
;     p0 = f32x16{}; p1 = f32x16{};
; #pragma unroll
;     for (int d0 = 0; d0 < 4; ++d0) { const int cb = (comp * 64 + d0 * 16 + hi * 8) * 2;
;         const bf16x8 b0 = *reinterpret_cast<const bf16x8*>(Ks + KSWZ(r32, cb));
;         const bf16x8 b1 = *reinterpret_cast<const bf16x8*>(Ks + KSWZ(32 + r32, cb));
;         p0 = __builtin_amdgcn_mfma_f32_32x32x16_bf16(b0, qr[d0], p0, 0, 0, 0);
;         p1 = __builtin_amdgcn_mfma_f32_32x32x16_bf16(b1, qr[d0], p1, 0, 0, 0); }
; }
.LBB0_280:
	ds_read_b128 v[64:67], v140 offset:49152
	ds_read_b128 v[68:71], v140 offset:57344
	v_add_f32_e32 v135, 0, v240
	v_add_f32_e32 v135, v241, v135
	v_add_f32_e32 v135, v242, v135
	s_waitcnt lgkmcnt(1)
	v_mfma_f32_32x32x16_bf16 v[80:95], v[64:67], v[110:113], 0
	v_add_f32_e32 v135, v243, v135
	v_add_f32_e32 v135, v244, v135
	ds_read_b128 v[136:139], v143 offset:49152
	ds_read_b128 v[178:181], v143 offset:57344
	v_add_f32_e32 v135, v245, v135
	v_add_f32_e32 v135, v246, v135
	v_add_f32_e32 v135, v247, v135
	v_add_f32_e32 v135, v248, v135
	s_waitcnt lgkmcnt(2)
	v_mfma_f32_32x32x16_bf16 v[64:79], v[68:71], v[110:113], 0
	v_add_f32_e32 v135, v249, v135
	v_add_f32_e32 v135, v250, v135
	v_add_f32_e32 v135, v251, v135
	v_exp_f32_e32 v128, v128
	v_add_f32_e32 v135, v206, v135
	v_exp_f32_e32 v129, v129
	v_add_f32_e32 v135, v207, v135
	s_waitcnt lgkmcnt(1)
	v_mfma_f32_32x32x16_bf16 v[80:95], v[136:139], v[106:109], v[80:95]
	v_exp_f32_e32 v126, v126
	v_add_f32_e32 v135, v208, v135
	v_exp_f32_e32 v127, v127
	v_add_f32_e32 v135, v209, v135
	v_exp_f32_e32 v122, v122
	v_add_f32_e32 v135, v128, v135
	v_exp_f32_e32 v123, v123
	s_waitcnt lgkmcnt(0)
	v_mfma_f32_32x32x16_bf16 v[64:79], v[178:181], v[106:109], v[64:79]
	ds_read_b128 v[136:139], v142 offset:49152
	ds_read_b128 v[178:181], v142 offset:57344
	v_add_f32_e32 v135, v129, v135
	v_exp_f32_e32 v118, v118
	v_add_f32_e32 v135, v126, v135
	v_exp_f32_e32 v119, v119
	v_add_f32_e32 v135, v127, v135
	v_exp_f32_e32 v116, v116
	s_waitcnt lgkmcnt(1)
	v_mfma_f32_32x32x16_bf16 v[80:95], v[136:139], v[102:105], v[80:95]
	v_add_f32_e32 v135, v122, v135
	v_exp_f32_e32 v117, v117
	v_add_f32_e32 v135, v123, v135
	v_exp_f32_e32 v124, v124
	v_add_f32_e32 v135, v118, v135
	v_exp_f32_e32 v125, v125
	v_add_f32_e32 v135, v119, v135
	s_waitcnt lgkmcnt(0)
	v_mfma_f32_32x32x16_bf16 v[64:79], v[178:181], v[102:105], v[64:79]
	ds_read_b128 v[136:139], v141 offset:49152
	ds_read_b128 v[178:181], v141 offset:57344
	v_exp_f32_e32 v120, v120
	v_add_f32_e32 v135, v116, v135
	v_exp_f32_e32 v121, v121
	v_add_f32_e32 v135, v117, v135
	v_exp_f32_e32 v114, v114
	v_add_f32_e32 v135, v124, v135
	s_waitcnt lgkmcnt(1)
	v_mfma_f32_32x32x16_bf16 v[80:95], v[136:139], v[98:101], v[80:95]
	v_exp_f32_e32 v115, v115
	v_add_f32_e32 v135, v125, v135
	v_add_f32_e32 v135, v120, v135
	v_add_f32_e32 v135, v121, v135
	v_add_f32_e32 v135, v114, v135
	v_add_f32_e32 v135, v115, v135
	v_mov_b32_e32 v136, v135
	s_waitcnt lgkmcnt(0)
	v_mfma_f32_32x32x16_bf16 v[64:79], v[178:181], v[98:101], v[64:79]
	v_permlane32_swap_b32_e32 v135, v136
	v_cvt_pk_bf16_f32 v178, v240, v241
	v_cvt_pk_bf16_f32 v179, v242, v243
	v_cvt_pk_bf16_f32 v180, v244, v245
	v_cvt_pk_bf16_f32 v181, v246, v247
	v_cvt_pk_bf16_f32 v144, v248, v249
	v_cvt_pk_bf16_f32 v145, v250, v251
	v_cvt_pk_bf16_f32 v146, v206, v207
	v_cvt_pk_bf16_f32 v147, v208, v209
	v_cvt_pk_bf16_f32 v166, v128, v129
	v_cvt_pk_bf16_f32 v167, v126, v127
	v_cvt_pk_bf16_f32 v168, v122, v123
	v_cvt_pk_bf16_f32 v169, v118, v119
	v_cvt_pk_bf16_f32 v170, v116, v117
	v_cvt_pk_bf16_f32 v171, v124, v125
	v_cvt_pk_bf16_f32 v172, v120, v121
	v_cvt_pk_bf16_f32 v173, v114, v115
	s_nop 0
	v_permlane32_swap_b32_e32 v178, v180
	v_permlane32_swap_b32_e32 v179, v181
	v_permlane32_swap_b32_e32 v144, v146
	v_permlane32_swap_b32_e32 v145, v147
	v_permlane32_swap_b32_e32 v166, v168
	v_permlane32_swap_b32_e32 v167, v169
	v_permlane32_swap_b32_e32 v170, v172
	v_permlane32_swap_b32_e32 v171, v173
	v_add_u32_e32 v122, 0x10000, v96
	global_load_dwordx4 v[240:243], v96, s[58:59]
	global_load_dwordx4 v[244:247], v96, s[28:29]
	global_load_dwordx4 v[206:209], v122, s[58:59]
	s_nop 0
	global_load_dwordx4 v[248:251], v122, s[28:29]
	ds_read_b64_tr_b16 v[174:175], v160 offset:0
	ds_read_b64_tr_b16 v[176:177], v160 offset:0x800
	ds_read_b64_tr_b16 v[182:183], v160 offset:0x1000
	ds_read_b64_tr_b16 v[184:185], v160 offset:0x1800
	ds_read_b64_tr_b16 v[186:187], v160 offset:0x2000
	ds_read_b64_tr_b16 v[188:189], v160 offset:0x2800
	ds_read_b64_tr_b16 v[212:213], v160 offset:0x3000
	ds_read_b64_tr_b16 v[214:215], v160 offset:0x3800
	s_waitcnt lgkmcnt(0)
	v_mfma_f32_32x32x16_bf16 v[48:63], v[178:181], v[174:177], v[48:63]
	ds_read_b64_tr_b16 v[174:175], v160 offset:0x200
	ds_read_b64_tr_b16 v[176:177], v160 offset:0xa00
	v_max_f32_e32 v137, v81, v81
	v_max_f32_e32 v138, v80, v80
	v_max_f32_e32 v137, v138, v137
	v_max3_f32 v137, v137, v82, v83
	v_max3_f32 v137, v137, v84, v85
	v_mfma_f32_32x32x16_bf16 v[48:63], v[144:147], v[182:185], v[48:63]
	ds_read_b64_tr_b16 v[182:183], v160 offset:0x1200
	ds_read_b64_tr_b16 v[184:185], v160 offset:0x1a00
	v_max3_f32 v137, v137, v86, v87
	v_max3_f32 v137, v137, v88, v89
	v_max3_f32 v137, v137, v90, v91
	v_max3_f32 v137, v137, v92, v93
	v_max3_f32 v137, v137, v94, v95
	v_mfma_f32_32x32x16_bf16 v[48:63], v[166:169], v[186:189], v[48:63]
	ds_read_b64_tr_b16 v[186:187], v160 offset:0x2200
	ds_read_b64_tr_b16 v[188:189], v160 offset:0x2a00
	v_max3_f32 v137, v137, v64, v65
	v_max3_f32 v137, v137, v66, v67
	v_max3_f32 v137, v137, v68, v69
	v_max3_f32 v137, v137, v70, v71
	v_max3_f32 v137, v137, v72, v73
	v_mfma_f32_32x32x16_bf16 v[48:63], v[170:173], v[212:215], v[48:63]
	ds_read_b64_tr_b16 v[212:213], v160 offset:0x3200
	ds_read_b64_tr_b16 v[214:215], v160 offset:0x3a00
	v_max3_f32 v137, v137, v74, v75
	v_max3_f32 v137, v137, v76, v77
	v_max3_f32 v137, v137, v78, v79
	v_mov_b32_e32 v138, v137
	s_nop 1
	v_permlane32_swap_b32_e32 v137, v138
	s_waitcnt lgkmcnt(0)
; __device__ __forceinline__ void partialSM(f32x16& p0, f32x16& p1, float& m_reg, float& mn, float& alpha) {
;     ...
;     { auto rr = __builtin_amdgcn_permlane32_swap(__float_as_uint(pmax), __float_as_uint(pmax), false, false);
;       pmax = fmaxf(__uint_as_float(rr[0]), __uint_as_float(rr[1])); }
;     if (__builtin_expect(__all(pmax - m_reg <= THR / SCALE), 1)) { mn = m_reg; alpha = 1.f; }
;     else { mn = fmaxf(m_reg, pmax); alpha = __builtin_amdgcn_exp2f((m_reg - mn) * C); m_reg = mn; }
;     const float mnC = -mn * C;
; #pragma unroll
;     for (int r = 0; r < 16; ++r) p0[r] = fmaf(p0[r], C, mnC);
; #pragma unroll
;     for (int r = 0; r < 16; ++r) p1[r] = fmaf(p1[r], C, mnC);
; #pragma unroll
;     for (int r = 0; r < 16; ++r) p0[r] = __builtin_amdgcn_exp2f(p0[r]);
; }
	v_mfma_f32_32x32x16_bf16 v[32:47], v[178:181], v[174:177], v[32:47]
	ds_read_b64_tr_b16 v[174:175], v160 offset:0x400
	ds_read_b64_tr_b16 v[176:177], v160 offset:0xc00
	v_max_f32_e32 v138, v138, v138
	v_max_f32_e32 v137, v137, v137
	v_max_f32_e32 v137, v137, v138
	v_sub_f32_e32 v138, v137, v134
	v_cmp_ge_f32_e32 vcc, s65, v138
	v_mfma_f32_32x32x16_bf16 v[32:47], v[144:147], v[182:185], v[32:47]
	ds_read_b64_tr_b16 v[182:183], v160 offset:0x1400
	ds_read_b64_tr_b16 v[184:185], v160 offset:0x1c00
	v_max_f32_e32 v138, v134, v134
	v_max_f32_e32 v137, v138, v137
	v_sub_f32_e32 v138, v134, v137
	v_mul_f32_e32 v138, 0x3e38aa3b, v138
	v_exp_f32_e32 v138, v138
	v_mfma_f32_32x32x16_bf16 v[32:47], v[166:169], v[186:189], v[32:47]
	ds_read_b64_tr_b16 v[186:187], v160 offset:0x2400
	ds_read_b64_tr_b16 v[188:189], v160 offset:0x2c00
	s_cmp_eq_u64 vcc, exec
	s_cselect_b64 s[8:9], -1, 0
	v_cndmask_b32_e64 v138, v138, 1.0, s[8:9]
	v_cndmask_b32_e64 v134, v137, v134, s[8:9]
	v_mul_f32_e32 v137, 0xbe38aa3b, v134
	v_mfma_f32_32x32x16_bf16 v[32:47], v[170:173], v[212:215], v[32:47]
	ds_read_b64_tr_b16 v[212:213], v160 offset:0x3400
	ds_read_b64_tr_b16 v[214:215], v160 offset:0x3c00
	v_pk_fma_f32 v[80:81], v[80:81], s[72:73], v[136:137] op_sel:[0,0,1] op_sel_hi:[1,0,1]
	v_pk_fma_f32 v[82:83], v[82:83], s[72:73], v[136:137] op_sel:[0,0,1] op_sel_hi:[1,0,1]
	v_pk_fma_f32 v[84:85], v[84:85], s[72:73], v[136:137] op_sel:[0,0,1] op_sel_hi:[1,0,1]
	v_pk_fma_f32 v[86:87], v[86:87], s[72:73], v[136:137] op_sel:[0,0,1] op_sel_hi:[1,0,1]
	v_pk_fma_f32 v[88:89], v[88:89], s[72:73], v[136:137] op_sel:[0,0,1] op_sel_hi:[1,0,1]
	s_waitcnt lgkmcnt(0)
	v_mfma_f32_32x32x16_bf16 v[16:31], v[178:181], v[174:177], v[16:31]
	ds_read_b64_tr_b16 v[174:175], v160 offset:0x600
	ds_read_b64_tr_b16 v[176:177], v160 offset:0xe00
	v_pk_fma_f32 v[90:91], v[90:91], s[72:73], v[136:137] op_sel:[0,0,1] op_sel_hi:[1,0,1]
	v_pk_fma_f32 v[92:93], v[92:93], s[72:73], v[136:137] op_sel:[0,0,1] op_sel_hi:[1,0,1]
	v_pk_fma_f32 v[94:95], v[94:95], s[72:73], v[136:137] op_sel:[0,0,1] op_sel_hi:[1,0,1]
	v_exp_f32_e32 v127, v80
	v_mfma_f32_32x32x16_bf16 v[16:31], v[144:147], v[182:185], v[16:31]
	ds_read_b64_tr_b16 v[182:183], v160 offset:0x1600
	ds_read_b64_tr_b16 v[184:185], v160 offset:0x1e00
	v_exp_f32_e32 v129, v81
	v_exp_f32_e32 v125, v82
	v_exp_f32_e32 v128, v83
	v_mfma_f32_32x32x16_bf16 v[16:31], v[166:169], v[186:189], v[16:31]
	ds_read_b64_tr_b16 v[186:187], v160 offset:0x2600
	ds_read_b64_tr_b16 v[188:189], v160 offset:0x2e00
	v_exp_f32_e32 v123, v84
	v_exp_f32_e32 v126, v85
	v_exp_f32_e32 v122, v86
	v_mfma_f32_32x32x16_bf16 v[16:31], v[170:173], v[212:215], v[16:31]
	ds_read_b64_tr_b16 v[212:213], v160 offset:0x3600
	ds_read_b64_tr_b16 v[214:215], v160 offset:0x3e00
	v_exp_f32_e32 v124, v87
	v_exp_f32_e32 v119, v88
	v_exp_f32_e32 v121, v89
	s_waitcnt lgkmcnt(0)
	v_mfma_f32_32x32x16_bf16 v[0:15], v[178:181], v[174:177], v[0:15]
	s_barrier
	s_waitcnt vmcnt(0)
	ds_write_b128 v163, v[240:243]
	ds_write_b128 v164, v[206:209]
	ds_write_b128 v161, v[244:247] offset:32768
	ds_write_b128 v162, v[248:251] offset:32768
	v_exp_f32_e32 v117, v90
	v_exp_f32_e32 v120, v91
	v_exp_f32_e32 v115, v92
	v_mfma_f32_32x32x16_bf16 v[0:15], v[144:147], v[182:185], v[0:15]
	v_exp_f32_e32 v118, v93
	v_exp_f32_e32 v114, v94
	v_exp_f32_e32 v116, v95
	v_mfma_f32_32x32x16_bf16 v[0:15], v[166:169], v[186:189], v[0:15]
	v_mfma_f32_32x32x16_bf16 v[0:15], v[170:173], v[212:215], v[0:15]
	v_cmp_gt_f32_e32 vcc, 1.0, v138
	s_cbranch_vccz .LBB0_284
	s_and_saveexec_b64 s[2:3], s[6:7]
	ds_write_b32 v157, v138 offset:128
	s_or_b64 exec, exec, s[2:3]
	s_waitcnt lgkmcnt(0)
	ds_read_b128 v[240:243], v158 offset:224
	ds_read_b128 v[244:247], v158 offset:192
	ds_read_b128 v[248:251], v158 offset:160
	ds_read_b128 v[206:209], v158 offset:128
	s_waitcnt lgkmcnt(3)
	v_pk_mul_f32 v[62:63], v[62:63], v[242:243]
	s_waitcnt lgkmcnt(2)
	v_pk_mul_f32 v[58:59], v[58:59], v[246:247]
	s_waitcnt lgkmcnt(1)
	v_pk_mul_f32 v[54:55], v[54:55], v[250:251]
	s_waitcnt lgkmcnt(0)
	v_pk_mul_f32 v[50:51], v[50:51], v[208:209]
	v_pk_mul_f32 v[60:61], v[60:61], v[240:241]
	v_pk_mul_f32 v[56:57], v[56:57], v[244:245]
	v_pk_mul_f32 v[52:53], v[52:53], v[248:249]
	v_pk_mul_f32 v[48:49], v[48:49], v[206:207]
	v_pk_mul_f32 v[46:47], v[46:47], v[242:243]
	v_pk_mul_f32 v[42:43], v[42:43], v[246:247]
	v_pk_mul_f32 v[38:39], v[38:39], v[250:251]
	v_pk_mul_f32 v[34:35], v[34:35], v[208:209]
	v_pk_mul_f32 v[44:45], v[44:45], v[240:241]
	v_pk_mul_f32 v[40:41], v[40:41], v[244:245]
	v_pk_mul_f32 v[36:37], v[36:37], v[248:249]
	v_pk_mul_f32 v[32:33], v[32:33], v[206:207]
	v_pk_mul_f32 v[30:31], v[30:31], v[242:243]
	v_pk_mul_f32 v[26:27], v[26:27], v[246:247]
	v_pk_mul_f32 v[22:23], v[22:23], v[250:251]
	v_pk_mul_f32 v[18:19], v[18:19], v[208:209]
	v_pk_mul_f32 v[28:29], v[28:29], v[240:241]
	v_pk_mul_f32 v[24:25], v[24:25], v[244:245]
	v_pk_mul_f32 v[20:21], v[20:21], v[248:249]
	v_pk_mul_f32 v[16:17], v[16:17], v[206:207]
	v_pk_mul_f32 v[14:15], v[14:15], v[242:243]
	v_pk_mul_f32 v[10:11], v[10:11], v[246:247]
	v_pk_mul_f32 v[6:7], v[6:7], v[250:251]
	v_pk_mul_f32 v[2:3], v[2:3], v[208:209]
	v_pk_mul_f32 v[12:13], v[12:13], v[240:241]
	v_pk_mul_f32 v[8:9], v[8:9], v[244:245]
	v_pk_mul_f32 v[4:5], v[4:5], v[248:249]
	v_pk_mul_f32 v[0:1], v[0:1], v[206:207]
; __device__ __forceinline__ void partialSM(f32x16& p0, f32x16& p1, float& m_reg, float& mn, float& alpha) {
;     constexpr float C = SCALE * 1.4426950408889634f;
;     float pmax = p0[0];
; #pragma unroll
;     for (int r = 1; r < 16; ++r) pmax = fmaxf(pmax, p0[r]);
; #pragma unroll
;     for (int r = 0; r < 16; ++r) pmax = fmaxf(pmax, p1[r]);
;     { auto rr = __builtin_amdgcn_permlane32_swap(__float_as_uint(pmax), __float_as_uint(pmax), false, false);
;       pmax = fmaxf(__uint_as_float(rr[0]), __uint_as_float(rr[1])); }
;     if (__builtin_expect(__all(pmax - m_reg <= THR / SCALE), 1)) { mn = m_reg; alpha = 1.f; }
;     else { mn = fmaxf(m_reg, pmax); alpha = __builtin_amdgcn_exp2f((m_reg - mn) * C); m_reg = mn; }
;     const float mnC = -mn * C;
; #pragma unroll
;     for (int r = 0; r < 16; ++r) p0[r] = fmaf(p0[r], C, mnC);
; #pragma unroll
;     for (int r = 0; r < 16; ++r) p1[r] = fmaf(p1[r], C, mnC);
; #pragma unroll
;     for (int r = 0; r < 16; ++r) p0[r] = __builtin_amdgcn_exp2f(p0[r]);
; }
; __device__ __forceinline__ void finishSM(f32x16& p0, f32x16& p1, float alpha, float& l_reg, bf16x8& pa0, bf16x8& pa1, bf16x8& pa2, bf16x8& pa3) {
; #pragma unroll
;     for (int r = 0; r < 16; ++r) p1[r] = __builtin_amdgcn_exp2f(p1[r]);
;     float ps = 0;
; #pragma unroll
;     for (int r = 0; r < 16; ++r) ps += p0[r];
; #pragma unroll
;     for (int r = 0; r < 16; ++r) ps += p1[r];
;     { auto rr = __builtin_amdgcn_permlane32_swap(__float_as_uint(ps), __float_as_uint(ps), false, false);
;       ps = __uint_as_float(rr[0]) + __uint_as_float(rr[1]); }
;     l_reg = l_reg * alpha + ps;
;     ...
;     PK4(p0, 0, pa0); PK4(p0, 8, pa1); PK4(p1, 0, pa2); PK4(p1, 8, pa3);
;     ...
; }
; __device__ __forceinline__ void qkt(f32x16& p0, f32x16& p1, const char* Ks, const bf16x8* qr, int r32, int hi, int comp) {
;     p0 = f32x16{}; p1 = f32x16{};
; #pragma unroll
;     for (int d0 = 0; d0 < 4; ++d0) { const int cb = (comp * 64 + d0 * 16 + hi * 8) * 2;
;         const bf16x8 b0 = *reinterpret_cast<const bf16x8*>(Ks + KSWZ(r32, cb));
;         const bf16x8 b1 = *reinterpret_cast<const bf16x8*>(Ks + KSWZ(32 + r32, cb));
;         p0 = __builtin_amdgcn_mfma_f32_32x32x16_bf16(b0, qr[d0], p0, 0, 0, 0);
;         p1 = __builtin_amdgcn_mfma_f32_32x32x16_bf16(b1, qr[d0], p1, 0, 0, 0); }
; }
.LBB0_284:
	v_fmamk_f32 v167, v64, 0x3e38aa3b, v137
	v_fmamk_f32 v168, v65, 0x3e38aa3b, v137
	v_fmamk_f32 v169, v66, 0x3e38aa3b, v137
	v_fmamk_f32 v170, v67, 0x3e38aa3b, v137
	v_fmamk_f32 v171, v68, 0x3e38aa3b, v137
	v_fmamk_f32 v144, v69, 0x3e38aa3b, v137
	v_fmamk_f32 v145, v70, 0x3e38aa3b, v137
	v_fmamk_f32 v146, v71, 0x3e38aa3b, v137
	v_fmamk_f32 v147, v72, 0x3e38aa3b, v137
	v_fmamk_f32 v148, v73, 0x3e38aa3b, v137
	v_fmamk_f32 v149, v74, 0x3e38aa3b, v137
	v_fmamk_f32 v166, v75, 0x3e38aa3b, v137
	v_fmamk_f32 v139, v76, 0x3e38aa3b, v137
	v_fmamk_f32 v172, v77, 0x3e38aa3b, v137
	v_fmamk_f32 v173, v78, 0x3e38aa3b, v137
	v_fmac_f32_e32 v137, 0x3e38aa3b, v79
	s_waitcnt lgkmcnt(0)
	s_barrier
	ds_read_b128 v[64:67], v140 offset:32768
	ds_read_b128 v[68:71], v140 offset:40960
	ds_read_b128 v[174:177], v143 offset:32768
	ds_read_b128 v[178:181], v143 offset:40960
	v_exp_f32_e32 v185, v139
	v_add_f32_e32 v139, 0, v127
	s_waitcnt lgkmcnt(3)
	v_mfma_f32_32x32x16_bf16 v[80:95], v[64:67], v[110:113], 0
	v_add_f32_e32 v139, v129, v139
	v_add_f32_e32 v139, v125, v139
	v_add_f32_e32 v139, v128, v139
	v_add_f32_e32 v139, v123, v139
	v_add_f32_e32 v139, v126, v139
	v_add_f32_e32 v139, v122, v139
	v_add_f32_e32 v139, v124, v139
	s_waitcnt lgkmcnt(2)
	v_mfma_f32_32x32x16_bf16 v[64:79], v[68:71], v[110:113], 0
	v_add_f32_e32 v139, v119, v139
	v_add_f32_e32 v139, v121, v139
	v_add_f32_e32 v139, v117, v139
	v_add_f32_e32 v139, v120, v139
	v_add_f32_e32 v139, v115, v139
	v_add_f32_e32 v139, v118, v139
	v_add_f32_e32 v139, v114, v139
	s_waitcnt lgkmcnt(1)
	v_mfma_f32_32x32x16_bf16 v[80:95], v[174:177], v[106:109], v[80:95]
	v_add_f32_e32 v139, v116, v139
	v_exp_f32_e32 v145, v145
	v_exp_f32_e32 v182, v148
	v_exp_f32_e32 v183, v149
	v_exp_f32_e32 v184, v166
	v_exp_f32_e32 v186, v172
	v_exp_f32_e32 v187, v173
	s_waitcnt lgkmcnt(0)
	v_mfma_f32_32x32x16_bf16 v[64:79], v[178:181], v[106:109], v[64:79]
	ds_read_b128 v[174:177], v142 offset:32768
	ds_read_b128 v[178:181], v142 offset:40960
	v_exp_f32_e32 v137, v137
	s_waitcnt lgkmcnt(1)
	v_mfma_f32_32x32x16_bf16 v[80:95], v[174:177], v[102:105], v[80:95]
	s_waitcnt lgkmcnt(0)
	v_mfma_f32_32x32x16_bf16 v[64:79], v[178:181], v[102:105], v[64:79]
	ds_read_b128 v[174:177], v141 offset:32768
	ds_read_b128 v[178:181], v141 offset:40960
	s_waitcnt lgkmcnt(1)
	v_mfma_f32_32x32x16_bf16 v[80:95], v[174:177], v[98:101], v[80:95]
	v_exp_f32_e32 v174, v167
	v_exp_f32_e32 v175, v168
	v_exp_f32_e32 v176, v169
	v_exp_f32_e32 v177, v170
	v_add_f32_e32 v139, v174, v139
	v_add_f32_e32 v139, v175, v139
	v_add_f32_e32 v139, v176, v139
	s_waitcnt lgkmcnt(0)
	v_mfma_f32_32x32x16_bf16 v[64:79], v[178:181], v[98:101], v[64:79]
	v_exp_f32_e32 v178, v171
	v_exp_f32_e32 v179, v144
	v_exp_f32_e32 v180, v146
	v_add_f32_e32 v139, v177, v139
	v_exp_f32_e32 v181, v147
	v_add_f32_e32 v139, v178, v139
	v_add_f32_e32 v139, v179, v139
	v_add_f32_e32 v139, v145, v139
	v_add_f32_e32 v139, v180, v139
	v_add_f32_e32 v139, v181, v139
	v_add_f32_e32 v139, v182, v139
	v_add_f32_e32 v139, v183, v139
	v_add_f32_e32 v139, v184, v139
	v_add_f32_e32 v139, v185, v139
	v_add_f32_e32 v139, v186, v139
	v_add_f32_e32 v139, v187, v139
	v_add_f32_e32 v139, v137, v139
	v_mov_b32_e32 v144, v139
	s_nop 1
	v_permlane32_swap_b32_e32 v139, v144
	v_cvt_pk_bf16_f32 v146, v127, v129
	v_cvt_pk_bf16_f32 v147, v125, v128
	v_cvt_pk_bf16_f32 v148, v123, v126
	v_cvt_pk_bf16_f32 v149, v122, v124
	v_cvt_pk_bf16_f32 v166, v119, v121
	v_cvt_pk_bf16_f32 v167, v117, v120
	v_cvt_pk_bf16_f32 v168, v115, v118
	v_cvt_pk_bf16_f32 v169, v114, v116
	v_cvt_pk_bf16_f32 v170, v174, v175
	v_cvt_pk_bf16_f32 v171, v176, v177
	v_cvt_pk_bf16_f32 v172, v178, v179
	v_cvt_pk_bf16_f32 v173, v145, v180
	v_cvt_pk_bf16_f32 v174, v181, v182
	v_cvt_pk_bf16_f32 v175, v183, v184
	v_cvt_pk_bf16_f32 v176, v185, v186
	v_cvt_pk_bf16_f32 v177, v187, v137
	s_nop 0
	v_permlane32_swap_b32_e32 v146, v148
	v_permlane32_swap_b32_e32 v147, v149
	v_permlane32_swap_b32_e32 v166, v168
	v_permlane32_swap_b32_e32 v167, v169
	v_permlane32_swap_b32_e32 v170, v172
	v_permlane32_swap_b32_e32 v171, v173
	v_permlane32_swap_b32_e32 v174, v176
	v_permlane32_swap_b32_e32 v175, v177
	v_add_u32_e32 v118, 0x20000, v96
	v_add_u32_e32 v122, 0x30000, v96
	global_load_dwordx4 v[114:117], v118, s[58:59]
	s_nop 0
	global_load_dwordx4 v[118:121], v118, s[28:29]
	s_nop 0
	global_load_dwordx4 v[126:129], v122, s[58:59]
	s_nop 0
	global_load_dwordx4 v[122:125], v122, s[28:29]
	ds_read_b64_tr_b16 v[178:179], v159 offset:0
	ds_read_b64_tr_b16 v[180:181], v159 offset:0x800
	ds_read_b64_tr_b16 v[182:183], v159 offset:0x1000
	ds_read_b64_tr_b16 v[184:185], v159 offset:0x1800
	ds_read_b64_tr_b16 v[186:187], v159 offset:0x2000
	ds_read_b64_tr_b16 v[188:189], v159 offset:0x2800
	ds_read_b64_tr_b16 v[212:213], v159 offset:0x3000
	ds_read_b64_tr_b16 v[214:215], v159 offset:0x3800
	s_waitcnt lgkmcnt(0)
	v_mfma_f32_32x32x16_bf16 v[48:63], v[146:149], v[178:181], v[48:63]
	ds_read_b64_tr_b16 v[178:179], v159 offset:0x200
	ds_read_b64_tr_b16 v[180:181], v159 offset:0xa00
	v_max_f32_e32 v255, v81, v81
	v_max_f32_e32 v210, v80, v80
	v_max_f32_e32 v255, v210, v255
	v_max3_f32 v255, v255, v82, v83
	v_max3_f32 v255, v255, v84, v85
	v_mfma_f32_32x32x16_bf16 v[48:63], v[166:169], v[182:185], v[48:63]
	ds_read_b64_tr_b16 v[182:183], v159 offset:0x1200
	ds_read_b64_tr_b16 v[184:185], v159 offset:0x1a00
	v_max3_f32 v255, v255, v86, v87
	v_max3_f32 v255, v255, v88, v89
	v_max3_f32 v255, v255, v90, v91
	v_max3_f32 v255, v255, v92, v93
	v_max3_f32 v255, v255, v94, v95
	v_mfma_f32_32x32x16_bf16 v[48:63], v[170:173], v[186:189], v[48:63]
	ds_read_b64_tr_b16 v[186:187], v159 offset:0x2200
	ds_read_b64_tr_b16 v[188:189], v159 offset:0x2a00
	v_max3_f32 v255, v255, v64, v65
	v_max3_f32 v255, v255, v66, v67
	v_max3_f32 v255, v255, v68, v69
	v_max3_f32 v255, v255, v70, v71
	v_max3_f32 v255, v255, v72, v73
	v_mfma_f32_32x32x16_bf16 v[48:63], v[174:177], v[212:215], v[48:63]
	ds_read_b64_tr_b16 v[212:213], v159 offset:0x3200
	ds_read_b64_tr_b16 v[214:215], v159 offset:0x3a00
	v_max3_f32 v255, v255, v74, v75
	v_max3_f32 v255, v255, v76, v77
	v_max3_f32 v255, v255, v78, v79
	v_mov_b32_e32 v210, v255
	s_nop 1
	v_permlane32_swap_b32_e32 v255, v210
	s_waitcnt lgkmcnt(0)
; __device__ __forceinline__ void partialSM(f32x16& p0, f32x16& p1, float& m_reg, float& mn, float& alpha) {
;     ...
;     { auto rr = __builtin_amdgcn_permlane32_swap(__float_as_uint(pmax), __float_as_uint(pmax), false, false);
;       pmax = fmaxf(__uint_as_float(rr[0]), __uint_as_float(rr[1])); }
;     if (__builtin_expect(__all(pmax - m_reg <= THR / SCALE), 1)) { mn = m_reg; alpha = 1.f; }
;     else { mn = fmaxf(m_reg, pmax); alpha = __builtin_amdgcn_exp2f((m_reg - mn) * C); m_reg = mn; }
;     const float mnC = -mn * C;
; #pragma unroll
;     for (int r = 0; r < 16; ++r) p0[r] = fmaf(p0[r], C, mnC);
; #pragma unroll
;     for (int r = 0; r < 16; ++r) p1[r] = fmaf(p1[r], C, mnC);
; #pragma unroll
;     for (int r = 0; r < 16; ++r) p0[r] = __builtin_amdgcn_exp2f(p0[r]);
; }
	v_mfma_f32_32x32x16_bf16 v[32:47], v[146:149], v[178:181], v[32:47]
	ds_read_b64_tr_b16 v[178:179], v159 offset:0x400
	ds_read_b64_tr_b16 v[180:181], v159 offset:0xc00
	v_max_f32_e32 v210, v210, v210
	v_max_f32_e32 v255, v255, v255
	v_max_f32_e32 v255, v255, v210
	v_sub_f32_e32 v210, v255, v134
	v_cmp_ge_f32_e32 vcc, s65, v210
	v_mfma_f32_32x32x16_bf16 v[32:47], v[166:169], v[182:185], v[32:47]
	ds_read_b64_tr_b16 v[182:183], v159 offset:0x1400
	ds_read_b64_tr_b16 v[184:185], v159 offset:0x1c00
	v_max_f32_e32 v210, v134, v134
	v_max_f32_e32 v210, v210, v255
	v_sub_f32_e32 v255, v134, v210
	v_mul_f32_e32 v255, 0x3e38aa3b, v255
	v_exp_f32_e32 v255, v255
	v_mfma_f32_32x32x16_bf16 v[32:47], v[170:173], v[186:189], v[32:47]
	ds_read_b64_tr_b16 v[186:187], v159 offset:0x2400
	ds_read_b64_tr_b16 v[188:189], v159 offset:0x2c00
	s_cmp_eq_u64 vcc, exec
	s_cselect_b64 s[8:9], -1, 0
	v_cndmask_b32_e64 v255, v255, 1.0, s[8:9]
	v_cndmask_b32_e64 v134, v210, v134, s[8:9]
	v_mul_f32_e32 v210, 0xbe38aa3b, v134
	v_mfma_f32_32x32x16_bf16 v[32:47], v[174:177], v[212:215], v[32:47]
	ds_read_b64_tr_b16 v[212:213], v159 offset:0x3400
	ds_read_b64_tr_b16 v[214:215], v159 offset:0x3c00
	v_pk_fma_f32 v[80:81], v[80:81], s[72:73], v[210:211] op_sel_hi:[1,0,0]
	v_pk_fma_f32 v[82:83], v[82:83], s[72:73], v[210:211] op_sel_hi:[1,0,0]
	v_pk_fma_f32 v[84:85], v[84:85], s[72:73], v[210:211] op_sel_hi:[1,0,0]
	v_pk_fma_f32 v[86:87], v[86:87], s[72:73], v[210:211] op_sel_hi:[1,0,0]
	v_pk_fma_f32 v[88:89], v[88:89], s[72:73], v[210:211] op_sel_hi:[1,0,0]
	s_waitcnt lgkmcnt(0)
	v_mfma_f32_32x32x16_bf16 v[16:31], v[146:149], v[178:181], v[16:31]
	ds_read_b64_tr_b16 v[178:179], v159 offset:0x600
	ds_read_b64_tr_b16 v[180:181], v159 offset:0xe00
	v_pk_fma_f32 v[90:91], v[90:91], s[72:73], v[210:211] op_sel_hi:[1,0,0]
	v_pk_fma_f32 v[92:93], v[92:93], s[72:73], v[210:211] op_sel_hi:[1,0,0]
	v_pk_fma_f32 v[94:95], v[94:95], s[72:73], v[210:211] op_sel_hi:[1,0,0]
	v_exp_f32_e32 v240, v80
	v_mfma_f32_32x32x16_bf16 v[16:31], v[166:169], v[182:185], v[16:31]
	ds_read_b64_tr_b16 v[182:183], v159 offset:0x1600
	ds_read_b64_tr_b16 v[184:185], v159 offset:0x1e00
	v_exp_f32_e32 v241, v81
	v_exp_f32_e32 v242, v82
	v_exp_f32_e32 v243, v83
	v_mfma_f32_32x32x16_bf16 v[16:31], v[170:173], v[186:189], v[16:31]
	ds_read_b64_tr_b16 v[186:187], v159 offset:0x2600
	ds_read_b64_tr_b16 v[188:189], v159 offset:0x2e00
	v_exp_f32_e32 v244, v84
	v_exp_f32_e32 v245, v85
	v_exp_f32_e32 v246, v86
	v_mfma_f32_32x32x16_bf16 v[16:31], v[174:177], v[212:215], v[16:31]
	ds_read_b64_tr_b16 v[212:213], v159 offset:0x3600
	ds_read_b64_tr_b16 v[214:215], v159 offset:0x3e00
	v_exp_f32_e32 v247, v87
	v_exp_f32_e32 v248, v88
	v_exp_f32_e32 v249, v89
	s_waitcnt lgkmcnt(0)
	v_mfma_f32_32x32x16_bf16 v[0:15], v[146:149], v[178:181], v[0:15]
	s_barrier
	s_waitcnt vmcnt(0)
	ds_write_b128 v163, v[114:117] offset:16384
	ds_write_b128 v164, v[126:129] offset:16384
	ds_write_b128 v161, v[118:121] offset:49152
	ds_write_b128 v162, v[122:125] offset:49152
	v_exp_f32_e32 v250, v90
	v_exp_f32_e32 v251, v91
	v_exp_f32_e32 v206, v92
	v_mfma_f32_32x32x16_bf16 v[0:15], v[166:169], v[182:185], v[0:15]
	v_exp_f32_e32 v207, v93
	v_exp_f32_e32 v208, v94
	v_exp_f32_e32 v209, v95
	v_mfma_f32_32x32x16_bf16 v[0:15], v[170:173], v[186:189], v[0:15]
	v_mfma_f32_32x32x16_bf16 v[0:15], v[174:177], v[212:215], v[0:15]
	v_mov_b32_e32 v137, v255
	v_cmp_gt_f32_e32 vcc, 1.0, v137
	s_cbranch_vccz .LBB0_288
	s_and_saveexec_b64 s[2:3], s[6:7]
	ds_write_b32 v157, v137 offset:128
	s_or_b64 exec, exec, s[2:3]
	s_waitcnt lgkmcnt(0)
	ds_read_b128 v[114:117], v158 offset:224
	ds_read_b128 v[118:121], v158 offset:192
	ds_read_b128 v[122:125], v158 offset:160
	ds_read_b128 v[126:129], v158 offset:128
	s_waitcnt lgkmcnt(3)
	v_pk_mul_f32 v[62:63], v[62:63], v[116:117]
	s_waitcnt lgkmcnt(2)
	v_pk_mul_f32 v[58:59], v[58:59], v[120:121]
	s_waitcnt lgkmcnt(1)
	v_pk_mul_f32 v[54:55], v[54:55], v[124:125]
	s_waitcnt lgkmcnt(0)
	v_pk_mul_f32 v[50:51], v[50:51], v[128:129]
	v_pk_mul_f32 v[60:61], v[60:61], v[114:115]
	v_pk_mul_f32 v[56:57], v[56:57], v[118:119]
	v_pk_mul_f32 v[52:53], v[52:53], v[122:123]
	v_pk_mul_f32 v[48:49], v[48:49], v[126:127]
	v_pk_mul_f32 v[46:47], v[46:47], v[116:117]
	v_pk_mul_f32 v[42:43], v[42:43], v[120:121]
	v_pk_mul_f32 v[38:39], v[38:39], v[124:125]
	v_pk_mul_f32 v[34:35], v[34:35], v[128:129]
	v_pk_mul_f32 v[44:45], v[44:45], v[114:115]
	v_pk_mul_f32 v[40:41], v[40:41], v[118:119]
	v_pk_mul_f32 v[36:37], v[36:37], v[122:123]
	v_pk_mul_f32 v[32:33], v[32:33], v[126:127]
	v_pk_mul_f32 v[30:31], v[30:31], v[116:117]
	v_pk_mul_f32 v[26:27], v[26:27], v[120:121]
	v_pk_mul_f32 v[22:23], v[22:23], v[124:125]
	v_pk_mul_f32 v[18:19], v[18:19], v[128:129]
	v_pk_mul_f32 v[28:29], v[28:29], v[114:115]
	v_pk_mul_f32 v[24:25], v[24:25], v[118:119]
	v_pk_mul_f32 v[20:21], v[20:21], v[122:123]
	v_pk_mul_f32 v[16:17], v[16:17], v[126:127]
	v_pk_mul_f32 v[14:15], v[14:15], v[116:117]
	v_pk_mul_f32 v[10:11], v[10:11], v[120:121]
	v_pk_mul_f32 v[6:7], v[6:7], v[124:125]
	v_pk_mul_f32 v[2:3], v[2:3], v[128:129]
	v_pk_mul_f32 v[12:13], v[12:13], v[114:115]
	v_pk_mul_f32 v[8:9], v[8:9], v[118:119]
	v_pk_mul_f32 v[4:5], v[4:5], v[122:123]
	v_pk_mul_f32 v[0:1], v[0:1], v[126:127]
